# prologue de-serialisation: SSD intra-chunk units issue their 12 B/C/xs staging loads and the dt load together (distinct registers, counted waits) instead of 13 serialized load-wait-write steps
# speedup vs baseline: 1.0032x; 1.0032x over previous
.LBB0_29:
	s_and_b32 s84, s3, 3
	s_lshl_b32 s50, s84, 3
	v_readlane_b32 s43, v255, 35
	s_add_i32 s50, s50, s43
	s_lshl_b32 s88, s50, 2
	v_mov_b32_e32 v0, s88
	s_waitcnt lgkmcnt(0)
	global_load_dword v2, v0, s[56:57]
	global_load_dword v67, v0, s[58:59]
	s_ashr_i32 s42, s3, 2
	s_lshl_b32 s49, s42, 6
	s_lshl_b32 s62, s84, 8
	s_mov_b32 s63, s89
	v_lshl_add_u64 v[6:7], v[26:27], 0, s[62:63]
	s_barrier
	v_lshl_add_u64 v[8:9], v[28:29], 0, s[62:63]
	s_ashr_i32 s43, s42, 31
	s_lshl_b64 s[42:43], s[42:43], 18
	s_lshl_b32 s62, s84, 16
	s_or_b32 s42, s42, s62
	s_waitcnt vmcnt(1)
	v_mul_f32_e32 v2, 0x3fb8aa3b, v2
	v_exp_f32_e32 v12, v2
	v_add_u32_e32 v2, s49, v42
	v_ashrrev_i32_e32 v3, 31, v2
	v_lshlrev_b64 v[10:11], 10, v[2:3]
	v_lshl_add_u64 v[2:3], v[6:7], 0, v[10:11]
	global_load_dwordx4 v[162:165], v[2:3], off
	v_lshl_add_u64 v[2:3], v[8:9], 0, v[10:11]
	global_load_dwordx4 v[166:169], v[2:3], off
	v_add_u32_e32 v2, s49, v33
	v_ashrrev_i32_e32 v3, 31, v2
	v_lshlrev_b64 v[10:11], 10, v[2:3]
	v_lshl_add_u64 v[2:3], v[6:7], 0, v[10:11]
	global_load_dwordx4 v[170:173], v[2:3], off
	v_lshl_add_u64 v[6:7], v[30:31], 0, s[42:43]
	s_movk_i32 s42, 0x2000
	v_lshl_add_u64 v[2:3], v[8:9], 0, v[10:11]
	global_load_dwordx4 v[174:177], v[2:3], off
	global_load_dwordx4 v[178:181], v[6:7], off
	v_add_co_u32_e64 v2, s[42:43], s42, v6
	s_nop 1
	v_addc_co_u32_e64 v3, s[42:43], 0, v7, s[42:43]
	global_load_dwordx4 v[182:185], v[2:3], off
	s_movk_i32 s42, 0x4000
	v_add_co_u32_e64 v2, s[42:43], s42, v6
	s_nop 1
	v_addc_co_u32_e64 v3, s[42:43], 0, v7, s[42:43]
	global_load_dwordx4 v[220:223], v[2:3], off
	s_movk_i32 s42, 0x6000
	v_add_co_u32_e64 v2, s[42:43], s42, v6
	s_nop 1
	v_addc_co_u32_e64 v3, s[42:43], 0, v7, s[42:43]
	global_load_dwordx4 v[224:227], v[2:3], off
	s_mov_b32 s42, 0x8000
	v_add_co_u32_e64 v2, s[42:43], s42, v6
	s_nop 1
	v_addc_co_u32_e64 v3, s[42:43], 0, v7, s[42:43]
	global_load_dwordx4 v[228:231], v[2:3], off
	s_mov_b32 s42, 0xa000
	v_add_co_u32_e64 v2, s[42:43], s42, v6
	s_nop 1
	v_addc_co_u32_e64 v3, s[42:43], 0, v7, s[42:43]
	global_load_dwordx4 v[232:235], v[2:3], off
	s_mov_b32 s42, 0xc000
	v_add_co_u32_e64 v2, s[42:43], s42, v6
	s_nop 1
	v_addc_co_u32_e64 v3, s[42:43], 0, v7, s[42:43]
	global_load_dwordx4 v[236:239], v[2:3], off
	s_mov_b32 s42, 0xe000
	v_add_co_u32_e64 v2, s[42:43], s42, v6
	s_nop 1
	v_addc_co_u32_e64 v3, s[42:43], 0, v7, s[42:43]
	global_load_dwordx4 v[240:243], v[2:3], off
	v_or_b32_e32 v2, s49, v158
	v_ashrrev_i32_e32 v3, 31, v2
	v_lshlrev_b64 v[2:3], 7, v[2:3]
	v_lshl_add_u64 v[2:3], s[46:47], 0, v[2:3]
	v_lshl_add_u64 v[2:3], v[2:3], 0, s[88:89]
	global_load_dword v0, v[2:3], off
	s_waitcnt vmcnt(12)
	ds_write_b128 v32, v[162:165]
	s_waitcnt vmcnt(11)
	ds_write_b128 v32, v[166:169] offset:17408
	s_waitcnt vmcnt(10)
	ds_write_b128 v34, v[170:173]
	s_waitcnt vmcnt(9)
	ds_write_b128 v34, v[174:177] offset:17408
	s_waitcnt vmcnt(8)
	ds_write_b128 v35, v[178:181] offset:34816
	s_waitcnt vmcnt(7)
	ds_write_b128 v35, v[182:185] offset:44032
	s_waitcnt vmcnt(6)
	ds_write_b128 v35, v[220:223] offset:53248
	s_waitcnt vmcnt(5)
	ds_write_b128 v35, v[224:227] offset:62464
	s_waitcnt vmcnt(4)
	ds_write_b128 v43, v[228:231] offset:36864
	s_waitcnt vmcnt(3)
	ds_write_b128 v43, v[232:235] offset:46080
	s_waitcnt vmcnt(2)
	ds_write_b128 v43, v[236:239] offset:55296
	s_waitcnt vmcnt(1)
	ds_write_b128 v43, v[240:243] offset:64512
	s_waitcnt vmcnt(0)
	v_mul_f32_e64 v2, v0, -v12
	ds_bpermute_b32 v3, v44, v2
	s_waitcnt lgkmcnt(0)
	v_fma_f32 v3, v0, -v12, v3
	v_cndmask_b32_e32 v2, v3, v2, vcc
	ds_bpermute_b32 v3, v45, v2
	s_waitcnt lgkmcnt(0)
	v_add_f32_e32 v3, v2, v3
	v_cndmask_b32_e64 v2, v3, v2, s[4:5]
	ds_bpermute_b32 v3, v46, v2
	s_waitcnt lgkmcnt(0)
	v_add_f32_e32 v3, v2, v3
	v_cndmask_b32_e64 v2, v3, v2, s[6:7]
	ds_bpermute_b32 v3, v47, v2
	s_waitcnt lgkmcnt(0)
	v_add_f32_e32 v3, v2, v3
	v_cndmask_b32_e64 v2, v3, v2, s[8:9]
	ds_bpermute_b32 v3, v48, v2
	s_waitcnt lgkmcnt(0)
	v_add_f32_e32 v3, v2, v3
	v_cndmask_b32_e64 v2, v3, v2, s[10:11]
	ds_bpermute_b32 v3, v49, v2
	s_waitcnt lgkmcnt(0)
	v_add_f32_e32 v3, v2, v3
	v_cndmask_b32_e64 v2, v3, v2, s[12:13]
	ds_write_b32 v39, v0
	ds_write_b32 v40, v2
	s_waitcnt lgkmcnt(0)
	s_barrier
	ds_read_b32 v0, v50
	ds_read_b128 v[2:5], v60 offset:17408
	ds_read_b128 v[6:9], v60
	s_waitcnt lgkmcnt(0)
	v_mfma_f32_16x16x32_bf16 v[2:5], v[6:9], v[2:5], 0
	ds_read_b128 v[6:9], v60 offset:17472
	ds_read_b128 v[10:13], v60 offset:64
	s_waitcnt lgkmcnt(0)
	v_mfma_f32_16x16x32_bf16 v[2:5], v[10:13], v[6:9], v[2:5]
	ds_read_b128 v[6:9], v60 offset:17536
	ds_read_b128 v[10:13], v60 offset:128
	s_waitcnt lgkmcnt(0)
	v_mfma_f32_16x16x32_bf16 v[2:5], v[10:13], v[6:9], v[2:5]
	ds_read_b128 v[6:9], v60 offset:17600
	ds_read_b128 v[10:13], v60 offset:192
	s_waitcnt lgkmcnt(0)
	v_mfma_f32_16x16x32_bf16 v[2:5], v[10:13], v[6:9], v[2:5]
	v_mov_b32_e32 v6, 0
	v_mov_b32_e32 v7, 0
	s_and_saveexec_b64 s[42:43], s[14:15]
	s_cbranch_execnz .LBB0_56
	s_or_b64 exec, exec, s[42:43]
	s_nop 2
	v_mov_b32_e32 v2, 0
	s_and_saveexec_b64 s[42:43], s[16:17]
	s_cbranch_execnz .LBB0_57
